# nt hint on the carry scan's read-once summary loads and write-once carry stores
# baseline (speedup 1.0000x reference)
; #define TIDX tid_opaque()
; DI void lru_carry_item(const Params& P, int it) {
;   const int ch = TIDX, dir = it & 1;
;   const size_t base = (size_t)it * 132 * 256 + ch;
;   float c = 0.f;
; #pragma unroll 4
;   for (int k = 0; k < 132; k++) {
;     int tile = dir == 0 ? k : (k < 4 ? 3 - k : 135 - k);
;     float2 s = P.lsum[base + (size_t)tile * 256];
;     P.lcar[base + (size_t)tile * 256] = c;
;     c = s.x * c + s.y;
;   }
; }
.LBB0_469:
	s_and_b64 s[4:5], s[82:83], exec
	s_cselect_b32 s8, 0, -1
	s_xor_b32 s6, s8, 0x800
	s_sub_u32 s6, s6, s8
	s_xor_b32 s7, s8, 0x400
	s_sub_u32 s7, s7, s8
	v_lshlrev_b32_e32 v156, 3, v0
	v_lshlrev_b32_e32 v157, 2, v0
	s_and_b32 s2, s8, 3
	s_lshl_b32 s2, s2, 11
	s_add_u32 s2, s70, s2
	s_addc_u32 s3, s71, 0
	s_and_b32 s4, s8, 3
	s_lshl_b32 s4, s4, 10
	s_add_u32 s4, s64, s4
	s_addc_u32 s5, s65, 0
	global_load_dwordx2 v[186:187], v156, s[2:3] nt
	s_add_u32 s2, s2, s6
	s_addc_u32 s3, s3, s8
	global_load_dwordx2 v[188:189], v156, s[2:3] nt
	s_add_u32 s2, s2, s6
	s_addc_u32 s3, s3, s8
	global_load_dwordx2 v[190:191], v156, s[2:3] nt
	s_add_u32 s2, s2, s6
	s_addc_u32 s3, s3, s8
	global_load_dwordx2 v[192:193], v156, s[2:3] nt
	s_add_u32 s2, s2, s6
	s_addc_u32 s3, s3, s8
	s_and_b32 s2, s8, 0x7f
	s_add_u32 s2, s2, 4
	s_lshl_b32 s2, s2, 11
	s_add_u32 s2, s70, s2
	s_addc_u32 s3, s71, 0
	global_load_dwordx2 v[194:195], v156, s[2:3] nt
	s_add_u32 s2, s2, s6
	s_addc_u32 s3, s3, s8
	global_load_dwordx2 v[196:197], v156, s[2:3] nt
	s_add_u32 s2, s2, s6
	s_addc_u32 s3, s3, s8
	global_load_dwordx2 v[198:199], v156, s[2:3] nt
	s_add_u32 s2, s2, s6
	s_addc_u32 s3, s3, s8
	global_load_dwordx2 v[200:201], v156, s[2:3] nt
	s_add_u32 s2, s2, s6
	s_addc_u32 s3, s3, s8
	global_load_dwordx2 v[202:203], v156, s[2:3] nt
	s_add_u32 s2, s2, s6
	s_addc_u32 s3, s3, s8
	global_load_dwordx2 v[204:205], v156, s[2:3] nt
	s_add_u32 s2, s2, s6
	s_addc_u32 s3, s3, s8
	global_load_dwordx2 v[206:207], v156, s[2:3] nt
	s_add_u32 s2, s2, s6
	s_addc_u32 s3, s3, s8
	global_load_dwordx2 v[208:209], v156, s[2:3] nt
	s_add_u32 s2, s2, s6
	s_addc_u32 s3, s3, s8
	global_load_dwordx2 v[210:211], v156, s[2:3] nt
	s_add_u32 s2, s2, s6
	s_addc_u32 s3, s3, s8
	global_load_dwordx2 v[212:213], v156, s[2:3] nt
	s_add_u32 s2, s2, s6
	s_addc_u32 s3, s3, s8
	global_load_dwordx2 v[214:215], v156, s[2:3] nt
	s_add_u32 s2, s2, s6
	s_addc_u32 s3, s3, s8
	global_load_dwordx2 v[216:217], v156, s[2:3] nt
	s_add_u32 s2, s2, s6
	s_addc_u32 s3, s3, s8
	global_load_dwordx2 v[218:219], v156, s[2:3] nt
	s_add_u32 s2, s2, s6
	s_addc_u32 s3, s3, s8
	global_load_dwordx2 v[220:221], v156, s[2:3] nt
	s_add_u32 s2, s2, s6
	s_addc_u32 s3, s3, s8
	global_load_dwordx2 v[222:223], v156, s[2:3] nt
	s_add_u32 s2, s2, s6
	s_addc_u32 s3, s3, s8
	global_load_dwordx2 v[224:225], v156, s[2:3] nt
	s_add_u32 s2, s2, s6
	s_addc_u32 s3, s3, s8
	global_load_dwordx2 v[226:227], v156, s[2:3] nt
	s_add_u32 s2, s2, s6
	s_addc_u32 s3, s3, s8
	global_load_dwordx2 v[228:229], v156, s[2:3] nt
	s_add_u32 s2, s2, s6
	s_addc_u32 s3, s3, s8
	global_load_dwordx2 v[230:231], v156, s[2:3] nt
	s_add_u32 s2, s2, s6
	s_addc_u32 s3, s3, s8
	global_load_dwordx2 v[232:233], v156, s[2:3] nt
	s_add_u32 s2, s2, s6
	s_addc_u32 s3, s3, s8
	global_load_dwordx2 v[234:235], v156, s[2:3] nt
	s_add_u32 s2, s2, s6
	s_addc_u32 s3, s3, s8
	global_load_dwordx2 v[236:237], v156, s[2:3] nt
	s_add_u32 s2, s2, s6
	s_addc_u32 s3, s3, s8
	global_load_dwordx2 v[238:239], v156, s[2:3] nt
	s_add_u32 s2, s2, s6
	s_addc_u32 s3, s3, s8
	global_load_dwordx2 v[240:241], v156, s[2:3] nt
	s_add_u32 s2, s2, s6
	s_addc_u32 s3, s3, s8
	global_load_dwordx2 v[242:243], v156, s[2:3] nt
	s_add_u32 s2, s2, s6
	s_addc_u32 s3, s3, s8
	global_load_dwordx2 v[244:245], v156, s[2:3] nt
	s_add_u32 s2, s2, s6
	s_addc_u32 s3, s3, s8
	global_load_dwordx2 v[246:247], v156, s[2:3] nt
	s_add_u32 s2, s2, s6
	s_addc_u32 s3, s3, s8
	global_load_dwordx2 v[248:249], v156, s[2:3] nt
	s_add_u32 s2, s2, s6
	s_addc_u32 s3, s3, s8
	global_load_dwordx2 v[250:251], v156, s[2:3] nt
	s_add_u32 s2, s2, s6
	s_addc_u32 s3, s3, s8
	s_waitcnt vmcnt(32)
	global_store_dword v157, v3, s[4:5] nt
	v_fma_f32 v158, v186, v3, v187
	s_add_u32 s4, s4, s7
	s_addc_u32 s5, s5, s8
	s_waitcnt vmcnt(32)
	global_store_dword v157, v158, s[4:5] nt
	v_fma_f32 v3, v188, v158, v189
	s_add_u32 s4, s4, s7
	s_addc_u32 s5, s5, s8
	s_waitcnt vmcnt(32)
	global_store_dword v157, v3, s[4:5] nt
	v_fma_f32 v158, v190, v3, v191
	s_add_u32 s4, s4, s7
	s_addc_u32 s5, s5, s8
	s_waitcnt vmcnt(32)
	global_store_dword v157, v158, s[4:5] nt
	v_fma_f32 v3, v192, v158, v193
	s_add_u32 s4, s4, s7
	s_addc_u32 s5, s5, s8
	s_and_b32 s4, s8, 0x7f
	s_add_u32 s4, s4, 4
	s_lshl_b32 s4, s4, 10
	s_add_u32 s4, s64, s4
	s_addc_u32 s5, s65, 0
	s_waitcnt vmcnt(32)
	global_store_dword v157, v3, s[4:5] nt
	v_fma_f32 v158, v194, v3, v195
	s_add_u32 s4, s4, s7
	s_addc_u32 s5, s5, s8
	s_waitcnt vmcnt(32)
	global_store_dword v157, v158, s[4:5] nt
	v_fma_f32 v3, v196, v158, v197
	s_add_u32 s4, s4, s7
	s_addc_u32 s5, s5, s8
	s_waitcnt vmcnt(32)
	global_store_dword v157, v3, s[4:5] nt
	v_fma_f32 v158, v198, v3, v199
	s_add_u32 s4, s4, s7
	s_addc_u32 s5, s5, s8
	s_waitcnt vmcnt(32)
	global_store_dword v157, v158, s[4:5] nt
	v_fma_f32 v3, v200, v158, v201
	s_add_u32 s4, s4, s7
	s_addc_u32 s5, s5, s8
	s_waitcnt vmcnt(32)
	global_store_dword v157, v3, s[4:5] nt
	v_fma_f32 v158, v202, v3, v203
	s_add_u32 s4, s4, s7
	s_addc_u32 s5, s5, s8
	s_waitcnt vmcnt(32)
	global_store_dword v157, v158, s[4:5] nt
	v_fma_f32 v3, v204, v158, v205
	s_add_u32 s4, s4, s7
	s_addc_u32 s5, s5, s8
	s_waitcnt vmcnt(32)
	global_store_dword v157, v3, s[4:5] nt
	v_fma_f32 v158, v206, v3, v207
	s_add_u32 s4, s4, s7
	s_addc_u32 s5, s5, s8
	s_waitcnt vmcnt(32)
	global_store_dword v157, v158, s[4:5] nt
	v_fma_f32 v3, v208, v158, v209
	s_add_u32 s4, s4, s7
	s_addc_u32 s5, s5, s8
	s_waitcnt vmcnt(32)
	global_store_dword v157, v3, s[4:5] nt
	v_fma_f32 v158, v210, v3, v211
	s_add_u32 s4, s4, s7
	s_addc_u32 s5, s5, s8
	s_waitcnt vmcnt(32)
	global_store_dword v157, v158, s[4:5] nt
	v_fma_f32 v3, v212, v158, v213
	s_add_u32 s4, s4, s7
	s_addc_u32 s5, s5, s8
	s_waitcnt vmcnt(32)
; DI void lru_carry_item(const Params& P, int it) {
;     ...
;   for (int k = 0; k < 132; k++) {
;     int tile = dir == 0 ? k : (k < 4 ? 3 - k : 135 - k);
;     float2 s = P.lsum[base + (size_t)tile * 256];
;     P.lcar[base + (size_t)tile * 256] = c;
;     c = s.x * c + s.y;
	global_store_dword v157, v3, s[4:5] nt
	v_fma_f32 v158, v214, v3, v215
	s_add_u32 s4, s4, s7
	s_addc_u32 s5, s5, s8
	s_waitcnt vmcnt(32)
	global_store_dword v157, v158, s[4:5] nt
	v_fma_f32 v3, v216, v158, v217
	s_add_u32 s4, s4, s7
	s_addc_u32 s5, s5, s8
	s_waitcnt vmcnt(32)
	global_store_dword v157, v3, s[4:5] nt
	v_fma_f32 v158, v218, v3, v219
	s_add_u32 s4, s4, s7
	s_addc_u32 s5, s5, s8
	s_waitcnt vmcnt(32)
	global_store_dword v157, v158, s[4:5] nt
	v_fma_f32 v3, v220, v158, v221
	s_add_u32 s4, s4, s7
	s_addc_u32 s5, s5, s8
	s_waitcnt vmcnt(32)
	global_store_dword v157, v3, s[4:5] nt
	v_fma_f32 v158, v222, v3, v223
	s_add_u32 s4, s4, s7
	s_addc_u32 s5, s5, s8
	s_waitcnt vmcnt(32)
	global_store_dword v157, v158, s[4:5] nt
	v_fma_f32 v3, v224, v158, v225
	s_add_u32 s4, s4, s7
	s_addc_u32 s5, s5, s8
	s_waitcnt vmcnt(32)
	global_store_dword v157, v3, s[4:5] nt
	v_fma_f32 v158, v226, v3, v227
	s_add_u32 s4, s4, s7
	s_addc_u32 s5, s5, s8
	s_waitcnt vmcnt(32)
	global_store_dword v157, v158, s[4:5] nt
	v_fma_f32 v3, v228, v158, v229
	s_add_u32 s4, s4, s7
	s_addc_u32 s5, s5, s8
	s_waitcnt vmcnt(32)
	global_store_dword v157, v3, s[4:5] nt
	v_fma_f32 v158, v230, v3, v231
	s_add_u32 s4, s4, s7
	s_addc_u32 s5, s5, s8
	s_waitcnt vmcnt(32)
	global_store_dword v157, v158, s[4:5] nt
	v_fma_f32 v3, v232, v158, v233
	s_add_u32 s4, s4, s7
	s_addc_u32 s5, s5, s8
	s_waitcnt vmcnt(32)
	global_store_dword v157, v3, s[4:5] nt
	v_fma_f32 v158, v234, v3, v235
	s_add_u32 s4, s4, s7
	s_addc_u32 s5, s5, s8
	s_waitcnt vmcnt(32)
	global_store_dword v157, v158, s[4:5] nt
	v_fma_f32 v3, v236, v158, v237
	s_add_u32 s4, s4, s7
	s_addc_u32 s5, s5, s8
	s_waitcnt vmcnt(32)
	global_store_dword v157, v3, s[4:5] nt
	v_fma_f32 v158, v238, v3, v239
	s_add_u32 s4, s4, s7
	s_addc_u32 s5, s5, s8
	s_waitcnt vmcnt(32)
	global_store_dword v157, v158, s[4:5] nt
	v_fma_f32 v3, v240, v158, v241
	s_add_u32 s4, s4, s7
	s_addc_u32 s5, s5, s8
	s_waitcnt vmcnt(32)
	global_store_dword v157, v3, s[4:5] nt
	v_fma_f32 v158, v242, v3, v243
	s_add_u32 s4, s4, s7
	s_addc_u32 s5, s5, s8
	s_waitcnt vmcnt(32)
	global_store_dword v157, v158, s[4:5] nt
	v_fma_f32 v3, v244, v158, v245
	s_add_u32 s4, s4, s7
	s_addc_u32 s5, s5, s8
	s_waitcnt vmcnt(32)
	global_store_dword v157, v3, s[4:5] nt
	v_fma_f32 v158, v246, v3, v247
	s_add_u32 s4, s4, s7
	s_addc_u32 s5, s5, s8
	s_waitcnt vmcnt(32)
	global_store_dword v157, v158, s[4:5] nt
	v_fma_f32 v3, v248, v158, v249
	s_add_u32 s4, s4, s7
	s_addc_u32 s5, s5, s8
	s_waitcnt vmcnt(32)
	global_store_dword v157, v3, s[4:5] nt
	v_fma_f32 v158, v250, v3, v251
	s_add_u32 s4, s4, s7
	s_addc_u32 s5, s5, s8
	global_load_dwordx2 v[186:187], v156, s[2:3] nt
	s_add_u32 s2, s2, s6
	s_addc_u32 s3, s3, s8
	global_load_dwordx2 v[188:189], v156, s[2:3] nt
	s_add_u32 s2, s2, s6
	s_addc_u32 s3, s3, s8
	global_load_dwordx2 v[190:191], v156, s[2:3] nt
	s_add_u32 s2, s2, s6
	s_addc_u32 s3, s3, s8
	global_load_dwordx2 v[192:193], v156, s[2:3] nt
	s_add_u32 s2, s2, s6
	s_addc_u32 s3, s3, s8
	global_load_dwordx2 v[194:195], v156, s[2:3] nt
	s_add_u32 s2, s2, s6
	s_addc_u32 s3, s3, s8
	global_load_dwordx2 v[196:197], v156, s[2:3] nt
	s_add_u32 s2, s2, s6
	s_addc_u32 s3, s3, s8
	global_load_dwordx2 v[198:199], v156, s[2:3] nt
	s_add_u32 s2, s2, s6
	s_addc_u32 s3, s3, s8
	global_load_dwordx2 v[200:201], v156, s[2:3] nt
	s_add_u32 s2, s2, s6
	s_addc_u32 s3, s3, s8
	global_load_dwordx2 v[202:203], v156, s[2:3] nt
	s_add_u32 s2, s2, s6
	s_addc_u32 s3, s3, s8
	global_load_dwordx2 v[204:205], v156, s[2:3] nt
	s_add_u32 s2, s2, s6
	s_addc_u32 s3, s3, s8
	global_load_dwordx2 v[206:207], v156, s[2:3] nt
	s_add_u32 s2, s2, s6
	s_addc_u32 s3, s3, s8
	global_load_dwordx2 v[208:209], v156, s[2:3] nt
	s_add_u32 s2, s2, s6
	s_addc_u32 s3, s3, s8
	global_load_dwordx2 v[210:211], v156, s[2:3] nt
	s_add_u32 s2, s2, s6
	s_addc_u32 s3, s3, s8
	global_load_dwordx2 v[212:213], v156, s[2:3] nt
	s_add_u32 s2, s2, s6
	s_addc_u32 s3, s3, s8
	global_load_dwordx2 v[214:215], v156, s[2:3] nt
	s_add_u32 s2, s2, s6
	s_addc_u32 s3, s3, s8
	global_load_dwordx2 v[216:217], v156, s[2:3] nt
	s_add_u32 s2, s2, s6
	s_addc_u32 s3, s3, s8
	global_load_dwordx2 v[218:219], v156, s[2:3] nt
	s_add_u32 s2, s2, s6
	s_addc_u32 s3, s3, s8
	global_load_dwordx2 v[220:221], v156, s[2:3] nt
	s_add_u32 s2, s2, s6
	s_addc_u32 s3, s3, s8
	global_load_dwordx2 v[222:223], v156, s[2:3] nt
	s_add_u32 s2, s2, s6
	s_addc_u32 s3, s3, s8
	global_load_dwordx2 v[224:225], v156, s[2:3] nt
	s_add_u32 s2, s2, s6
	s_addc_u32 s3, s3, s8
	global_load_dwordx2 v[226:227], v156, s[2:3] nt
	s_add_u32 s2, s2, s6
	s_addc_u32 s3, s3, s8
	global_load_dwordx2 v[228:229], v156, s[2:3] nt
	s_add_u32 s2, s2, s6
	s_addc_u32 s3, s3, s8
	global_load_dwordx2 v[230:231], v156, s[2:3] nt
	s_add_u32 s2, s2, s6
	s_addc_u32 s3, s3, s8
	global_load_dwordx2 v[232:233], v156, s[2:3] nt
	s_add_u32 s2, s2, s6
	s_addc_u32 s3, s3, s8
	global_load_dwordx2 v[234:235], v156, s[2:3] nt
	s_add_u32 s2, s2, s6
	s_addc_u32 s3, s3, s8
	global_load_dwordx2 v[236:237], v156, s[2:3] nt
	s_add_u32 s2, s2, s6
	s_addc_u32 s3, s3, s8
	global_load_dwordx2 v[238:239], v156, s[2:3] nt
	s_add_u32 s2, s2, s6
	s_addc_u32 s3, s3, s8
	global_load_dwordx2 v[240:241], v156, s[2:3] nt
	s_add_u32 s2, s2, s6
	s_addc_u32 s3, s3, s8
	global_load_dwordx2 v[242:243], v156, s[2:3] nt
	s_add_u32 s2, s2, s6
	s_addc_u32 s3, s3, s8
	global_load_dwordx2 v[244:245], v156, s[2:3] nt
	s_add_u32 s2, s2, s6
	s_addc_u32 s3, s3, s8
	global_load_dwordx2 v[246:247], v156, s[2:3] nt
	s_add_u32 s2, s2, s6
	s_addc_u32 s3, s3, s8
	global_load_dwordx2 v[248:249], v156, s[2:3] nt
	s_add_u32 s2, s2, s6
	s_addc_u32 s3, s3, s8
	global_load_dwordx2 v[250:251], v156, s[2:3] nt
	s_add_u32 s2, s2, s6
	s_addc_u32 s3, s3, s8
	s_waitcnt vmcnt(32)
; DI void lru_carry_item(const Params& P, int it) {
;     ...
;   for (int k = 0; k < 132; k++) {
;     int tile = dir == 0 ? k : (k < 4 ? 3 - k : 135 - k);
;     float2 s = P.lsum[base + (size_t)tile * 256];
;     P.lcar[base + (size_t)tile * 256] = c;
;     c = s.x * c + s.y;
	global_store_dword v157, v158, s[4:5] nt
	v_fma_f32 v3, v186, v158, v187
	s_add_u32 s4, s4, s7
	s_addc_u32 s5, s5, s8
	s_waitcnt vmcnt(32)
	global_store_dword v157, v3, s[4:5] nt
	v_fma_f32 v158, v188, v3, v189
	s_add_u32 s4, s4, s7
	s_addc_u32 s5, s5, s8
	s_waitcnt vmcnt(32)
	global_store_dword v157, v158, s[4:5] nt
	v_fma_f32 v3, v190, v158, v191
	s_add_u32 s4, s4, s7
	s_addc_u32 s5, s5, s8
	s_waitcnt vmcnt(32)
	global_store_dword v157, v3, s[4:5] nt
	v_fma_f32 v158, v192, v3, v193
	s_add_u32 s4, s4, s7
	s_addc_u32 s5, s5, s8
	s_waitcnt vmcnt(32)
	global_store_dword v157, v158, s[4:5] nt
	v_fma_f32 v3, v194, v158, v195
	s_add_u32 s4, s4, s7
	s_addc_u32 s5, s5, s8
	s_waitcnt vmcnt(32)
	global_store_dword v157, v3, s[4:5] nt
	v_fma_f32 v158, v196, v3, v197
	s_add_u32 s4, s4, s7
	s_addc_u32 s5, s5, s8
	s_waitcnt vmcnt(32)
	global_store_dword v157, v158, s[4:5] nt
	v_fma_f32 v3, v198, v158, v199
	s_add_u32 s4, s4, s7
	s_addc_u32 s5, s5, s8
	s_waitcnt vmcnt(32)
	global_store_dword v157, v3, s[4:5] nt
	v_fma_f32 v158, v200, v3, v201
	s_add_u32 s4, s4, s7
	s_addc_u32 s5, s5, s8
	s_waitcnt vmcnt(32)
	global_store_dword v157, v158, s[4:5] nt
	v_fma_f32 v3, v202, v158, v203
	s_add_u32 s4, s4, s7
	s_addc_u32 s5, s5, s8
	s_waitcnt vmcnt(32)
	global_store_dword v157, v3, s[4:5] nt
	v_fma_f32 v158, v204, v3, v205
	s_add_u32 s4, s4, s7
	s_addc_u32 s5, s5, s8
	s_waitcnt vmcnt(32)
	global_store_dword v157, v158, s[4:5] nt
	v_fma_f32 v3, v206, v158, v207
	s_add_u32 s4, s4, s7
	s_addc_u32 s5, s5, s8
	s_waitcnt vmcnt(32)
	global_store_dword v157, v3, s[4:5] nt
	v_fma_f32 v158, v208, v3, v209
	s_add_u32 s4, s4, s7
	s_addc_u32 s5, s5, s8
	s_waitcnt vmcnt(32)
	global_store_dword v157, v158, s[4:5] nt
	v_fma_f32 v3, v210, v158, v211
	s_add_u32 s4, s4, s7
	s_addc_u32 s5, s5, s8
	s_waitcnt vmcnt(32)
	global_store_dword v157, v3, s[4:5] nt
	v_fma_f32 v158, v212, v3, v213
	s_add_u32 s4, s4, s7
	s_addc_u32 s5, s5, s8
	s_waitcnt vmcnt(32)
	global_store_dword v157, v158, s[4:5] nt
	v_fma_f32 v3, v214, v158, v215
	s_add_u32 s4, s4, s7
	s_addc_u32 s5, s5, s8
	s_waitcnt vmcnt(32)
	global_store_dword v157, v3, s[4:5] nt
	v_fma_f32 v158, v216, v3, v217
	s_add_u32 s4, s4, s7
	s_addc_u32 s5, s5, s8
	s_waitcnt vmcnt(32)
	global_store_dword v157, v158, s[4:5] nt
	v_fma_f32 v3, v218, v158, v219
	s_add_u32 s4, s4, s7
	s_addc_u32 s5, s5, s8
	s_waitcnt vmcnt(32)
	global_store_dword v157, v3, s[4:5] nt
	v_fma_f32 v158, v220, v3, v221
	s_add_u32 s4, s4, s7
	s_addc_u32 s5, s5, s8
	s_waitcnt vmcnt(32)
	global_store_dword v157, v158, s[4:5] nt
	v_fma_f32 v3, v222, v158, v223
	s_add_u32 s4, s4, s7
	s_addc_u32 s5, s5, s8
	s_waitcnt vmcnt(32)
	global_store_dword v157, v3, s[4:5] nt
	v_fma_f32 v158, v224, v3, v225
	s_add_u32 s4, s4, s7
	s_addc_u32 s5, s5, s8
	s_waitcnt vmcnt(32)
	global_store_dword v157, v158, s[4:5] nt
	v_fma_f32 v3, v226, v158, v227
	s_add_u32 s4, s4, s7
	s_addc_u32 s5, s5, s8
	s_waitcnt vmcnt(32)
	global_store_dword v157, v3, s[4:5] nt
	v_fma_f32 v158, v228, v3, v229
	s_add_u32 s4, s4, s7
	s_addc_u32 s5, s5, s8
	s_waitcnt vmcnt(32)
	global_store_dword v157, v158, s[4:5] nt
	v_fma_f32 v3, v230, v158, v231
	s_add_u32 s4, s4, s7
	s_addc_u32 s5, s5, s8
	s_waitcnt vmcnt(32)
	global_store_dword v157, v3, s[4:5] nt
	v_fma_f32 v158, v232, v3, v233
	s_add_u32 s4, s4, s7
	s_addc_u32 s5, s5, s8
	s_waitcnt vmcnt(32)
	global_store_dword v157, v158, s[4:5] nt
	v_fma_f32 v3, v234, v158, v235
	s_add_u32 s4, s4, s7
	s_addc_u32 s5, s5, s8
	s_waitcnt vmcnt(32)
	global_store_dword v157, v3, s[4:5] nt
	v_fma_f32 v158, v236, v3, v237
	s_add_u32 s4, s4, s7
	s_addc_u32 s5, s5, s8
	s_waitcnt vmcnt(32)
	global_store_dword v157, v158, s[4:5] nt
	v_fma_f32 v3, v238, v158, v239
	s_add_u32 s4, s4, s7
	s_addc_u32 s5, s5, s8
	s_waitcnt vmcnt(32)
	global_store_dword v157, v3, s[4:5] nt
	v_fma_f32 v158, v240, v3, v241
	s_add_u32 s4, s4, s7
	s_addc_u32 s5, s5, s8
	s_waitcnt vmcnt(32)
	global_store_dword v157, v158, s[4:5] nt
	v_fma_f32 v3, v242, v158, v243
	s_add_u32 s4, s4, s7
	s_addc_u32 s5, s5, s8
	s_waitcnt vmcnt(32)
	global_store_dword v157, v3, s[4:5] nt
	v_fma_f32 v158, v244, v3, v245
	s_add_u32 s4, s4, s7
	s_addc_u32 s5, s5, s8
	s_waitcnt vmcnt(32)
	global_store_dword v157, v158, s[4:5] nt
	v_fma_f32 v3, v246, v158, v247
	s_add_u32 s4, s4, s7
	s_addc_u32 s5, s5, s8
	s_waitcnt vmcnt(32)
	global_store_dword v157, v3, s[4:5] nt
	v_fma_f32 v158, v248, v3, v249
	s_add_u32 s4, s4, s7
	s_addc_u32 s5, s5, s8
	s_waitcnt vmcnt(32)
; DI void lru_carry_item(const Params& P, int it) {
;     ...
;   for (int k = 0; k < 132; k++) {
;     int tile = dir == 0 ? k : (k < 4 ? 3 - k : 135 - k);
;     float2 s = P.lsum[base + (size_t)tile * 256];
;     P.lcar[base + (size_t)tile * 256] = c;
;     c = s.x * c + s.y;
	global_store_dword v157, v158, s[4:5] nt
	v_fma_f32 v3, v250, v158, v251
	s_add_u32 s4, s4, s7
	s_addc_u32 s5, s5, s8
	global_load_dwordx2 v[186:187], v156, s[2:3] nt
	s_add_u32 s2, s2, s6
	s_addc_u32 s3, s3, s8
	global_load_dwordx2 v[188:189], v156, s[2:3] nt
	s_add_u32 s2, s2, s6
	s_addc_u32 s3, s3, s8
	global_load_dwordx2 v[190:191], v156, s[2:3] nt
	s_add_u32 s2, s2, s6
	s_addc_u32 s3, s3, s8
	global_load_dwordx2 v[192:193], v156, s[2:3] nt
	s_add_u32 s2, s2, s6
	s_addc_u32 s3, s3, s8
	global_load_dwordx2 v[194:195], v156, s[2:3] nt
	s_add_u32 s2, s2, s6
	s_addc_u32 s3, s3, s8
	global_load_dwordx2 v[196:197], v156, s[2:3] nt
	s_add_u32 s2, s2, s6
	s_addc_u32 s3, s3, s8
	global_load_dwordx2 v[198:199], v156, s[2:3] nt
	s_add_u32 s2, s2, s6
	s_addc_u32 s3, s3, s8
	global_load_dwordx2 v[200:201], v156, s[2:3] nt
	s_add_u32 s2, s2, s6
	s_addc_u32 s3, s3, s8
	global_load_dwordx2 v[202:203], v156, s[2:3] nt
	s_add_u32 s2, s2, s6
	s_addc_u32 s3, s3, s8
	global_load_dwordx2 v[204:205], v156, s[2:3] nt
	s_add_u32 s2, s2, s6
	s_addc_u32 s3, s3, s8
	global_load_dwordx2 v[206:207], v156, s[2:3] nt
	s_add_u32 s2, s2, s6
	s_addc_u32 s3, s3, s8
	global_load_dwordx2 v[208:209], v156, s[2:3] nt
	s_add_u32 s2, s2, s6
	s_addc_u32 s3, s3, s8
	global_load_dwordx2 v[210:211], v156, s[2:3] nt
	s_add_u32 s2, s2, s6
	s_addc_u32 s3, s3, s8
	global_load_dwordx2 v[212:213], v156, s[2:3] nt
	s_add_u32 s2, s2, s6
	s_addc_u32 s3, s3, s8
	global_load_dwordx2 v[214:215], v156, s[2:3] nt
	s_add_u32 s2, s2, s6
	s_addc_u32 s3, s3, s8
	global_load_dwordx2 v[216:217], v156, s[2:3] nt
	s_add_u32 s2, s2, s6
	s_addc_u32 s3, s3, s8
	global_load_dwordx2 v[218:219], v156, s[2:3] nt
	s_add_u32 s2, s2, s6
	s_addc_u32 s3, s3, s8
	global_load_dwordx2 v[220:221], v156, s[2:3] nt
	s_add_u32 s2, s2, s6
	s_addc_u32 s3, s3, s8
	global_load_dwordx2 v[222:223], v156, s[2:3] nt
	s_add_u32 s2, s2, s6
	s_addc_u32 s3, s3, s8
	global_load_dwordx2 v[224:225], v156, s[2:3] nt
	s_add_u32 s2, s2, s6
	s_addc_u32 s3, s3, s8
	global_load_dwordx2 v[226:227], v156, s[2:3] nt
	s_add_u32 s2, s2, s6
	s_addc_u32 s3, s3, s8
	global_load_dwordx2 v[228:229], v156, s[2:3] nt
	s_add_u32 s2, s2, s6
	s_addc_u32 s3, s3, s8
	global_load_dwordx2 v[230:231], v156, s[2:3] nt
	s_add_u32 s2, s2, s6
	s_addc_u32 s3, s3, s8
	global_load_dwordx2 v[232:233], v156, s[2:3] nt
	s_add_u32 s2, s2, s6
	s_addc_u32 s3, s3, s8
	global_load_dwordx2 v[234:235], v156, s[2:3] nt
	s_add_u32 s2, s2, s6
	s_addc_u32 s3, s3, s8
	global_load_dwordx2 v[236:237], v156, s[2:3] nt
	s_add_u32 s2, s2, s6
	s_addc_u32 s3, s3, s8
	global_load_dwordx2 v[238:239], v156, s[2:3] nt
	s_add_u32 s2, s2, s6
	s_addc_u32 s3, s3, s8
	global_load_dwordx2 v[240:241], v156, s[2:3] nt
	s_add_u32 s2, s2, s6
	s_addc_u32 s3, s3, s8
	global_load_dwordx2 v[242:243], v156, s[2:3] nt
	s_add_u32 s2, s2, s6
	s_addc_u32 s3, s3, s8
	global_load_dwordx2 v[244:245], v156, s[2:3] nt
	s_add_u32 s2, s2, s6
	s_addc_u32 s3, s3, s8
	global_load_dwordx2 v[246:247], v156, s[2:3] nt
	s_add_u32 s2, s2, s6
	s_addc_u32 s3, s3, s8
	global_load_dwordx2 v[248:249], v156, s[2:3] nt
	s_add_u32 s2, s2, s6
	s_addc_u32 s3, s3, s8
	global_load_dwordx2 v[250:251], v156, s[2:3] nt
	s_add_u32 s2, s2, s6
	s_addc_u32 s3, s3, s8
	s_waitcnt vmcnt(32)
	global_store_dword v157, v3, s[4:5] nt
	v_fma_f32 v158, v186, v3, v187
	s_add_u32 s4, s4, s7
	s_addc_u32 s5, s5, s8
	s_waitcnt vmcnt(32)
	global_store_dword v157, v158, s[4:5] nt
	v_fma_f32 v3, v188, v158, v189
	s_add_u32 s4, s4, s7
	s_addc_u32 s5, s5, s8
	s_waitcnt vmcnt(32)
	global_store_dword v157, v3, s[4:5] nt
	v_fma_f32 v158, v190, v3, v191
	s_add_u32 s4, s4, s7
	s_addc_u32 s5, s5, s8
	s_waitcnt vmcnt(32)
	global_store_dword v157, v158, s[4:5] nt
	v_fma_f32 v3, v192, v158, v193
	s_add_u32 s4, s4, s7
	s_addc_u32 s5, s5, s8
	s_waitcnt vmcnt(32)
	global_store_dword v157, v3, s[4:5] nt
	v_fma_f32 v158, v194, v3, v195
	s_add_u32 s4, s4, s7
	s_addc_u32 s5, s5, s8
	s_waitcnt vmcnt(32)
	global_store_dword v157, v158, s[4:5] nt
	v_fma_f32 v3, v196, v158, v197
	s_add_u32 s4, s4, s7
	s_addc_u32 s5, s5, s8
	s_waitcnt vmcnt(32)
	global_store_dword v157, v3, s[4:5] nt
	v_fma_f32 v158, v198, v3, v199
	s_add_u32 s4, s4, s7
	s_addc_u32 s5, s5, s8
	s_waitcnt vmcnt(32)
	global_store_dword v157, v158, s[4:5] nt
	v_fma_f32 v3, v200, v158, v201
	s_add_u32 s4, s4, s7
	s_addc_u32 s5, s5, s8
	s_waitcnt vmcnt(32)
	global_store_dword v157, v3, s[4:5] nt
	v_fma_f32 v158, v202, v3, v203
	s_add_u32 s4, s4, s7
	s_addc_u32 s5, s5, s8
	s_waitcnt vmcnt(32)
	global_store_dword v157, v158, s[4:5] nt
	v_fma_f32 v3, v204, v158, v205
	s_add_u32 s4, s4, s7
	s_addc_u32 s5, s5, s8
	s_waitcnt vmcnt(32)
	global_store_dword v157, v3, s[4:5] nt
	v_fma_f32 v158, v206, v3, v207
	s_add_u32 s4, s4, s7
	s_addc_u32 s5, s5, s8
	s_waitcnt vmcnt(32)
	global_store_dword v157, v158, s[4:5] nt
	v_fma_f32 v3, v208, v158, v209
	s_add_u32 s4, s4, s7
	s_addc_u32 s5, s5, s8
	s_waitcnt vmcnt(32)
	global_store_dword v157, v3, s[4:5] nt
	v_fma_f32 v158, v210, v3, v211
	s_add_u32 s4, s4, s7
	s_addc_u32 s5, s5, s8
	s_waitcnt vmcnt(32)
	global_store_dword v157, v158, s[4:5] nt
	v_fma_f32 v3, v212, v158, v213
	s_add_u32 s4, s4, s7
	s_addc_u32 s5, s5, s8
	s_waitcnt vmcnt(32)
	global_store_dword v157, v3, s[4:5] nt
	v_fma_f32 v158, v214, v3, v215
	s_add_u32 s4, s4, s7
	s_addc_u32 s5, s5, s8
	s_waitcnt vmcnt(32)
	global_store_dword v157, v158, s[4:5] nt
	v_fma_f32 v3, v216, v158, v217
	s_add_u32 s4, s4, s7
	s_addc_u32 s5, s5, s8
	s_waitcnt vmcnt(32)
	global_store_dword v157, v3, s[4:5] nt
	v_fma_f32 v158, v218, v3, v219
	s_add_u32 s4, s4, s7
	s_addc_u32 s5, s5, s8
	s_waitcnt vmcnt(32)
; DI void lru_carry_item(const Params& P, int it) {
;     ...
;   for (int k = 0; k < 132; k++) {
;     int tile = dir == 0 ? k : (k < 4 ? 3 - k : 135 - k);
;     float2 s = P.lsum[base + (size_t)tile * 256];
;     P.lcar[base + (size_t)tile * 256] = c;
;     c = s.x * c + s.y;
	global_store_dword v157, v158, s[4:5] nt
	v_fma_f32 v3, v220, v158, v221
	s_add_u32 s4, s4, s7
	s_addc_u32 s5, s5, s8
	s_waitcnt vmcnt(32)
	global_store_dword v157, v3, s[4:5] nt
	v_fma_f32 v158, v222, v3, v223
	s_add_u32 s4, s4, s7
	s_addc_u32 s5, s5, s8
	s_waitcnt vmcnt(32)
	global_store_dword v157, v158, s[4:5] nt
	v_fma_f32 v3, v224, v158, v225
	s_add_u32 s4, s4, s7
	s_addc_u32 s5, s5, s8
	s_waitcnt vmcnt(32)
	global_store_dword v157, v3, s[4:5] nt
	v_fma_f32 v158, v226, v3, v227
	s_add_u32 s4, s4, s7
	s_addc_u32 s5, s5, s8
	s_waitcnt vmcnt(32)
	global_store_dword v157, v158, s[4:5] nt
	v_fma_f32 v3, v228, v158, v229
	s_add_u32 s4, s4, s7
	s_addc_u32 s5, s5, s8
	s_waitcnt vmcnt(32)
	global_store_dword v157, v3, s[4:5] nt
	v_fma_f32 v158, v230, v3, v231
	s_add_u32 s4, s4, s7
	s_addc_u32 s5, s5, s8
	s_waitcnt vmcnt(32)
	global_store_dword v157, v158, s[4:5] nt
	v_fma_f32 v3, v232, v158, v233
	s_add_u32 s4, s4, s7
	s_addc_u32 s5, s5, s8
	s_waitcnt vmcnt(32)
	global_store_dword v157, v3, s[4:5] nt
	v_fma_f32 v158, v234, v3, v235
	s_add_u32 s4, s4, s7
	s_addc_u32 s5, s5, s8
	s_waitcnt vmcnt(32)
	global_store_dword v157, v158, s[4:5] nt
	v_fma_f32 v3, v236, v158, v237
	s_add_u32 s4, s4, s7
	s_addc_u32 s5, s5, s8
	s_waitcnt vmcnt(32)
	global_store_dword v157, v3, s[4:5] nt
	v_fma_f32 v158, v238, v3, v239
	s_add_u32 s4, s4, s7
	s_addc_u32 s5, s5, s8
	s_waitcnt vmcnt(32)
	global_store_dword v157, v158, s[4:5] nt
	v_fma_f32 v3, v240, v158, v241
	s_add_u32 s4, s4, s7
	s_addc_u32 s5, s5, s8
	s_waitcnt vmcnt(32)
	global_store_dword v157, v3, s[4:5] nt
	v_fma_f32 v158, v242, v3, v243
	s_add_u32 s4, s4, s7
	s_addc_u32 s5, s5, s8
	s_waitcnt vmcnt(32)
	global_store_dword v157, v158, s[4:5] nt
	v_fma_f32 v3, v244, v158, v245
	s_add_u32 s4, s4, s7
	s_addc_u32 s5, s5, s8
	s_waitcnt vmcnt(32)
	global_store_dword v157, v3, s[4:5] nt
	v_fma_f32 v158, v246, v3, v247
	s_add_u32 s4, s4, s7
	s_addc_u32 s5, s5, s8
	s_waitcnt vmcnt(32)
	global_store_dword v157, v158, s[4:5] nt
	v_fma_f32 v3, v248, v158, v249
	s_add_u32 s4, s4, s7
	s_addc_u32 s5, s5, s8
	s_waitcnt vmcnt(32)
	global_store_dword v157, v3, s[4:5] nt
	v_fma_f32 v158, v250, v3, v251
	s_add_u32 s4, s4, s7
	s_addc_u32 s5, s5, s8
	global_load_dwordx2 v[186:187], v156, s[2:3] nt
	s_add_u32 s2, s2, s6
	s_addc_u32 s3, s3, s8
	global_load_dwordx2 v[188:189], v156, s[2:3] nt
	s_add_u32 s2, s2, s6
	s_addc_u32 s3, s3, s8
	global_load_dwordx2 v[190:191], v156, s[2:3] nt
	s_add_u32 s2, s2, s6
	s_addc_u32 s3, s3, s8
	global_load_dwordx2 v[192:193], v156, s[2:3] nt
	s_add_u32 s2, s2, s6
	s_addc_u32 s3, s3, s8
	global_load_dwordx2 v[194:195], v156, s[2:3] nt
	s_add_u32 s2, s2, s6
	s_addc_u32 s3, s3, s8
	global_load_dwordx2 v[196:197], v156, s[2:3] nt
	s_add_u32 s2, s2, s6
	s_addc_u32 s3, s3, s8
	global_load_dwordx2 v[198:199], v156, s[2:3] nt
	s_add_u32 s2, s2, s6
	s_addc_u32 s3, s3, s8
	global_load_dwordx2 v[200:201], v156, s[2:3] nt
	s_add_u32 s2, s2, s6
	s_addc_u32 s3, s3, s8
	global_load_dwordx2 v[202:203], v156, s[2:3] nt
	s_add_u32 s2, s2, s6
	s_addc_u32 s3, s3, s8
	global_load_dwordx2 v[204:205], v156, s[2:3] nt
	s_add_u32 s2, s2, s6
	s_addc_u32 s3, s3, s8
	global_load_dwordx2 v[206:207], v156, s[2:3] nt
	s_add_u32 s2, s2, s6
	s_addc_u32 s3, s3, s8
	global_load_dwordx2 v[208:209], v156, s[2:3] nt
	s_add_u32 s2, s2, s6
	s_addc_u32 s3, s3, s8
	global_load_dwordx2 v[210:211], v156, s[2:3] nt
	s_add_u32 s2, s2, s6
	s_addc_u32 s3, s3, s8
	global_load_dwordx2 v[212:213], v156, s[2:3] nt
	s_add_u32 s2, s2, s6
	s_addc_u32 s3, s3, s8
	global_load_dwordx2 v[214:215], v156, s[2:3] nt
	s_add_u32 s2, s2, s6
	s_addc_u32 s3, s3, s8
	global_load_dwordx2 v[216:217], v156, s[2:3] nt
	s_add_u32 s2, s2, s6
	s_addc_u32 s3, s3, s8
	global_load_dwordx2 v[218:219], v156, s[2:3] nt
	s_add_u32 s2, s2, s6
	s_addc_u32 s3, s3, s8
	global_load_dwordx2 v[220:221], v156, s[2:3] nt
	s_add_u32 s2, s2, s6
	s_addc_u32 s3, s3, s8
	global_load_dwordx2 v[222:223], v156, s[2:3] nt
	s_add_u32 s2, s2, s6
	s_addc_u32 s3, s3, s8
	global_load_dwordx2 v[224:225], v156, s[2:3] nt
	s_add_u32 s2, s2, s6
	s_addc_u32 s3, s3, s8
	global_load_dwordx2 v[226:227], v156, s[2:3] nt
	s_add_u32 s2, s2, s6
	s_addc_u32 s3, s3, s8
	global_load_dwordx2 v[228:229], v156, s[2:3] nt
	s_add_u32 s2, s2, s6
	s_addc_u32 s3, s3, s8
	global_load_dwordx2 v[230:231], v156, s[2:3] nt
	s_add_u32 s2, s2, s6
	s_addc_u32 s3, s3, s8
	global_load_dwordx2 v[232:233], v156, s[2:3] nt
	s_add_u32 s2, s2, s6
	s_addc_u32 s3, s3, s8
	global_load_dwordx2 v[234:235], v156, s[2:3] nt
	s_add_u32 s2, s2, s6
	s_addc_u32 s3, s3, s8
	global_load_dwordx2 v[236:237], v156, s[2:3] nt
	s_add_u32 s2, s2, s6
	s_addc_u32 s3, s3, s8
	global_load_dwordx2 v[238:239], v156, s[2:3] nt
	s_add_u32 s2, s2, s6
	s_addc_u32 s3, s3, s8
	global_load_dwordx2 v[240:241], v156, s[2:3] nt
	s_add_u32 s2, s2, s6
	s_addc_u32 s3, s3, s8
	global_load_dwordx2 v[242:243], v156, s[2:3] nt
	s_add_u32 s2, s2, s6
	s_addc_u32 s3, s3, s8
	global_load_dwordx2 v[244:245], v156, s[2:3] nt
	s_add_u32 s2, s2, s6
	s_addc_u32 s3, s3, s8
	global_load_dwordx2 v[246:247], v156, s[2:3] nt
	s_add_u32 s2, s2, s6
	s_addc_u32 s3, s3, s8
	global_load_dwordx2 v[248:249], v156, s[2:3] nt
	s_add_u32 s2, s2, s6
	s_addc_u32 s3, s3, s8
	global_load_dwordx2 v[250:251], v156, s[2:3] nt
	s_add_u32 s2, s2, s6
	s_addc_u32 s3, s3, s8
	s_waitcnt vmcnt(32)
; DI void lru_carry_item(const Params& P, int it) {
;     ...
;   for (int k = 0; k < 132; k++) {
;     int tile = dir == 0 ? k : (k < 4 ? 3 - k : 135 - k);
;     float2 s = P.lsum[base + (size_t)tile * 256];
;     P.lcar[base + (size_t)tile * 256] = c;
;     c = s.x * c + s.y;
; DI void mix_phase(const Params& P, int l, char* smem, int* s_item, int qi) {
;     ...
;           lru_carry_item(P, gridDim.x - 1 - blockIdx.x);
	global_store_dword v157, v158, s[4:5] nt
	v_fma_f32 v3, v186, v158, v187
	s_add_u32 s4, s4, s7
	s_addc_u32 s5, s5, s8
	s_waitcnt vmcnt(32)
	global_store_dword v157, v3, s[4:5] nt
	v_fma_f32 v158, v188, v3, v189
	s_add_u32 s4, s4, s7
	s_addc_u32 s5, s5, s8
	s_waitcnt vmcnt(32)
	global_store_dword v157, v158, s[4:5] nt
	v_fma_f32 v3, v190, v158, v191
	s_add_u32 s4, s4, s7
	s_addc_u32 s5, s5, s8
	s_waitcnt vmcnt(32)
	global_store_dword v157, v3, s[4:5] nt
	v_fma_f32 v158, v192, v3, v193
	s_add_u32 s4, s4, s7
	s_addc_u32 s5, s5, s8
	s_waitcnt vmcnt(32)
	global_store_dword v157, v158, s[4:5] nt
	v_fma_f32 v3, v194, v158, v195
	s_add_u32 s4, s4, s7
	s_addc_u32 s5, s5, s8
	s_waitcnt vmcnt(32)
	global_store_dword v157, v3, s[4:5] nt
	v_fma_f32 v158, v196, v3, v197
	s_add_u32 s4, s4, s7
	s_addc_u32 s5, s5, s8
	s_waitcnt vmcnt(32)
	global_store_dword v157, v158, s[4:5] nt
	v_fma_f32 v3, v198, v158, v199
	s_add_u32 s4, s4, s7
	s_addc_u32 s5, s5, s8
	s_waitcnt vmcnt(32)
	global_store_dword v157, v3, s[4:5] nt
	v_fma_f32 v158, v200, v3, v201
	s_add_u32 s4, s4, s7
	s_addc_u32 s5, s5, s8
	s_waitcnt vmcnt(32)
	global_store_dword v157, v158, s[4:5] nt
	v_fma_f32 v3, v202, v158, v203
	s_add_u32 s4, s4, s7
	s_addc_u32 s5, s5, s8
	s_waitcnt vmcnt(32)
	global_store_dword v157, v3, s[4:5] nt
	v_fma_f32 v158, v204, v3, v205
	s_add_u32 s4, s4, s7
	s_addc_u32 s5, s5, s8
	s_waitcnt vmcnt(32)
	global_store_dword v157, v158, s[4:5] nt
	v_fma_f32 v3, v206, v158, v207
	s_add_u32 s4, s4, s7
	s_addc_u32 s5, s5, s8
	s_waitcnt vmcnt(32)
	global_store_dword v157, v3, s[4:5] nt
	v_fma_f32 v158, v208, v3, v209
	s_add_u32 s4, s4, s7
	s_addc_u32 s5, s5, s8
	s_waitcnt vmcnt(32)
	global_store_dword v157, v158, s[4:5] nt
	v_fma_f32 v3, v210, v158, v211
	s_add_u32 s4, s4, s7
	s_addc_u32 s5, s5, s8
	s_waitcnt vmcnt(32)
	global_store_dword v157, v3, s[4:5] nt
	v_fma_f32 v158, v212, v3, v213
	s_add_u32 s4, s4, s7
	s_addc_u32 s5, s5, s8
	s_waitcnt vmcnt(32)
	global_store_dword v157, v158, s[4:5] nt
	v_fma_f32 v3, v214, v158, v215
	s_add_u32 s4, s4, s7
	s_addc_u32 s5, s5, s8
	s_waitcnt vmcnt(32)
	global_store_dword v157, v3, s[4:5] nt
	v_fma_f32 v158, v216, v3, v217
	s_add_u32 s4, s4, s7
	s_addc_u32 s5, s5, s8
	s_waitcnt vmcnt(32)
	global_store_dword v157, v158, s[4:5] nt
	v_fma_f32 v3, v218, v158, v219
	s_add_u32 s4, s4, s7
	s_addc_u32 s5, s5, s8
	s_waitcnt vmcnt(32)
	global_store_dword v157, v3, s[4:5] nt
	v_fma_f32 v158, v220, v3, v221
	s_add_u32 s4, s4, s7
	s_addc_u32 s5, s5, s8
	s_waitcnt vmcnt(32)
	global_store_dword v157, v158, s[4:5] nt
	v_fma_f32 v3, v222, v158, v223
	s_add_u32 s4, s4, s7
	s_addc_u32 s5, s5, s8
	s_waitcnt vmcnt(32)
	global_store_dword v157, v3, s[4:5] nt
	v_fma_f32 v158, v224, v3, v225
	s_add_u32 s4, s4, s7
	s_addc_u32 s5, s5, s8
	s_waitcnt vmcnt(32)
	global_store_dword v157, v158, s[4:5] nt
	v_fma_f32 v3, v226, v158, v227
	s_add_u32 s4, s4, s7
	s_addc_u32 s5, s5, s8
	s_waitcnt vmcnt(32)
	global_store_dword v157, v3, s[4:5] nt
	v_fma_f32 v158, v228, v3, v229
	s_add_u32 s4, s4, s7
	s_addc_u32 s5, s5, s8
	s_waitcnt vmcnt(32)
	global_store_dword v157, v158, s[4:5] nt
	v_fma_f32 v3, v230, v158, v231
	s_add_u32 s4, s4, s7
	s_addc_u32 s5, s5, s8
	s_waitcnt vmcnt(32)
	global_store_dword v157, v3, s[4:5] nt
	v_fma_f32 v158, v232, v3, v233
	s_add_u32 s4, s4, s7
	s_addc_u32 s5, s5, s8
	s_waitcnt vmcnt(32)
	global_store_dword v157, v158, s[4:5] nt
	v_fma_f32 v3, v234, v158, v235
	s_add_u32 s4, s4, s7
	s_addc_u32 s5, s5, s8
	s_waitcnt vmcnt(32)
	global_store_dword v157, v3, s[4:5] nt
	v_fma_f32 v158, v236, v3, v237
	s_add_u32 s4, s4, s7
	s_addc_u32 s5, s5, s8
	s_waitcnt vmcnt(32)
	global_store_dword v157, v158, s[4:5] nt
	v_fma_f32 v3, v238, v158, v239
	s_add_u32 s4, s4, s7
	s_addc_u32 s5, s5, s8
	s_waitcnt vmcnt(32)
	global_store_dword v157, v3, s[4:5] nt
	v_fma_f32 v158, v240, v3, v241
	s_add_u32 s4, s4, s7
	s_addc_u32 s5, s5, s8
	s_waitcnt vmcnt(32)
	global_store_dword v157, v158, s[4:5] nt
	v_fma_f32 v3, v242, v158, v243
	s_add_u32 s4, s4, s7
	s_addc_u32 s5, s5, s8
	s_waitcnt vmcnt(32)
	global_store_dword v157, v3, s[4:5] nt
	v_fma_f32 v158, v244, v3, v245
	s_add_u32 s4, s4, s7
	s_addc_u32 s5, s5, s8
	s_waitcnt vmcnt(32)
	global_store_dword v157, v158, s[4:5] nt
	v_fma_f32 v3, v246, v158, v247
	s_add_u32 s4, s4, s7
	s_addc_u32 s5, s5, s8
	s_waitcnt vmcnt(32)
	global_store_dword v157, v3, s[4:5] nt
	v_fma_f32 v158, v248, v3, v249
	s_add_u32 s4, s4, s7
	s_addc_u32 s5, s5, s8
	s_waitcnt vmcnt(32)
	global_store_dword v157, v158, s[4:5] nt
	v_fma_f32 v3, v250, v158, v251
	s_add_u32 s4, s4, s7
	s_addc_u32 s5, s5, s8
	s_branch .LBB0_410
